# s5 chunk-carry scan spread over 8 workgroups (128 states each), idle waves stream the inputs; prep workgroups start at 40
# baseline (speedup 1.0000x reference)
.LBB0_105:
	s_or_b64 exec, exec, s[8:9]
	s_cmpk_lt_i32 s2, 0x2c0
	s_cselect_b64 s[0:1], -1, 0
	v_writelane_b32 v254, s0, 1
	s_ashr_i32 s3, s2, 31
	s_ashr_i32 s35, s34, 31
	v_writelane_b32 v254, s1, 2
	s_lshr_b32 s0, s3, 29
	s_add_i32 s0, s2, s0
	s_ashr_i32 s6, s0, 3
	s_and_b32 s0, s0, -8
	s_sub_i32 s0, s2, s0
	s_cmpk_lt_i32 s2, 0x200
	s_mul_i32 s76, s5, s4
	s_cselect_b64 s[4:5], -1, 0
	v_writelane_b32 v254, s4, 3
	s_cmpk_lt_i32 s2, 0x100
	s_movk_i32 s91, 0x59
	v_writelane_b32 v254, s5, 4
	s_cselect_b64 s[4:5], -1, 0
	v_writelane_b32 v254, s4, 5
	s_cmp_gt_i32 s2, 31
	s_mul_i32 s7, s0, 33
	v_writelane_b32 v254, s5, 6
	s_cselect_b64 s[4:5], -1, 0
	v_writelane_b32 v254, s4, 7
	s_movk_i32 s90, 0x400
	v_add_u32_e32 v0, 64, v31
	v_writelane_b32 v254, s5, 8
	v_cmp_lt_i32_e32 vcc, v30, v0
	v_readlane_b32 s1, v254, 0
	s_addk_i32 s1, 0xc000
	s_cmp_gt_i32 s2, 39
	v_writelane_b32 v254, s1, 9
	s_cselect_b64 s[4:5], -1, 0
	v_writelane_b32 v254, s4, 10
	s_add_i32 s1, s33, 0xfffffec0
	s_add_i32 s38, s10, 0xfffffec0
	v_writelane_b32 v254, s5, 11
	v_writelane_b32 v254, s1, 12
	s_lshl_b32 s1, s2, 5
	v_writelane_b32 v254, s1, 13
	s_and_b32 s1, s1, 0xffffff80
	v_writelane_b32 v254, s1, 14
	s_lshl_b32 s1, s2, 6
	s_sub_i32 s79, s34, 40
	v_writelane_b32 v254, s1, 15
	s_and_b32 s1, s1, 0xc0
	s_lshl_b64 s[12:13], s[2:3], 14
	s_lshl_b32 s4, s0, 5
	s_cmpk_lt_i32 s2, 0x400
	s_cselect_b64 s[8:9], -1, 0
	s_lshl_b32 s5, s0, 7
	v_writelane_b32 v254, s8, 16
	s_cmp_lt_i32 s0, 0
	s_cselect_b32 s7, s7, s4
	v_writelane_b32 v254, s9, 17
	s_cselect_b32 s9, s91, 0x58
	s_mul_i32 s8, s0, 0x81
	s_mul_i32 s0, s0, s9
	s_cselect_b32 s8, s8, s5
	s_add_i32 s0, s0, s6
	s_mul_hi_i32 s4, s0, 0x2e8ba2e9
	s_lshr_b32 s5, s4, 31
	s_ashr_i32 s4, s4, 4
	s_add_i32 s4, s4, s5
	s_mul_i32 s5, s4, 0x58
	s_sub_i32 s5, s0, s5
	s_bfe_i32 s0, s5, 0x80000
	s_bfe_u32 s0, s0, 0x3000c
	s_add_i32 s9, s5, s0
	s_bfe_i32 s0, s9, 0x80000
	s_and_b32 s9, s9, 0xf8
	s_sub_i32 s5, s5, s9
	s_lshl_b32 s4, s4, 3
	s_sext_i32_i16 s10, s0
	s_sext_i32_i8 s5, s5
	s_add_i32 s14, s4, s5
	s_ashr_i32 s4, s10, 3
	v_writelane_b32 v254, s4, 18
	s_mov_b32 s4, s14
	s_ashr_i32 s15, s14, 31
	v_writelane_b32 v254, s4, 19
	s_lshr_b32 s0, s10, 3
	s_lshl_b32 s93, s34, 5
	v_writelane_b32 v254, s5, 20
	s_lshl_b64 s[4:5], s[14:15], 19
	v_writelane_b32 v254, s4, 21
	s_lshl_b32 s94, s34, 6
	s_mul_hi_i32 s63, s38, 0xc00
	v_writelane_b32 v254, s5, 22
	s_bfe_i64 s[4:5], s[0:1], 0x100000
	s_lshl_b64 s[4:5], s[4:5], 19
	v_writelane_b32 v254, s4, 23
	s_add_i32 s0, s7, s6
	s_mul_i32 s62, s38, 0xc00
	v_writelane_b32 v254, s5, 24
	s_ashr_i32 s4, s0, 31
	s_lshr_b32 s4, s4, 27
	s_add_i32 s4, s0, s4
	s_ashr_i32 s5, s4, 5
	s_and_b32 s4, s4, 0xffe0
	s_sub_i32 s4, s0, s4
	s_bfe_i32 s0, s4, 0x80000
	s_bfe_u32 s0, s0, 0x3000c
	s_add_i32 s7, s4, s0
	s_bfe_i32 s0, s7, 0x80000
	s_and_b32 s7, s7, 0xf8
	s_sub_i32 s4, s4, s7
	s_lshl_b32 s5, s5, 3
	s_sext_i32_i8 s4, s4
	s_add_i32 s10, s5, s4
	s_add_i32 s4, s8, s6
	s_ashr_i32 s5, s4, 31
	s_lshr_b32 s5, s5, 25
	s_add_i32 s5, s4, s5
	s_ashr_i32 s6, s5, 7
	s_and_b32 s5, s5, 0xff80
	s_sub_i32 s5, s4, s5
	s_bfe_i32 s4, s5, 0x80000
	s_bfe_u32 s4, s4, 0x3000c
	s_add_i32 s7, s5, s4
	s_bfe_i32 s4, s7, 0x80000
	s_and_b32 s7, s7, 0xf8
	s_sub_i32 s5, s5, s7
	s_lshl_b32 s6, s6, 3
	s_sext_i32_i16 s8, s4
	s_sext_i32_i8 s5, s5
	s_add_i32 s14, s6, s5
	s_ashr_i32 s5, s8, 3
	v_writelane_b32 v254, s5, 25
	s_mov_b32 s6, s14
	s_ashr_i32 s15, s14, 31
	v_writelane_b32 v254, s6, 26
	s_lshr_b32 s4, s8, 3
	s_bfe_i64 s[4:5], s[4:5], 0x100000
	v_writelane_b32 v254, s7, 27
	s_lshl_b64 s[6:7], s[14:15], 19
	v_writelane_b32 v254, s6, 28
	s_lshl_b64 s[4:5], s[4:5], 19
	s_ashr_i32 s11, s10, 31
	v_writelane_b32 v254, s7, 29
	v_writelane_b32 v254, s4, 30
	s_sext_i32_i16 s9, s0
	s_lshr_b32 s0, s9, 3
	v_writelane_b32 v254, s5, 31
	s_lshl_b64 s[4:5], s[10:11], 19
	v_writelane_b32 v254, s4, 32
	s_ashr_i32 s92, s9, 3
	v_cndmask_b32_e32 v2, v173, v30, vcc
	v_writelane_b32 v254, s5, 33
	s_bfe_i64 s[4:5], s[0:1], 0x100000
	s_lshl_b64 s[6:7], s[4:5], 19
	v_writelane_b32 v254, s6, 34
	s_mov_b32 s0, s10
	s_lshl_b64 s[4:5], s[4:5], 21
	v_writelane_b32 v254, s7, 35
	v_writelane_b32 v254, s0, 36
	s_lshl_b64 s[6:7], s[10:11], 21
	v_cmp_lt_i32_e32 vcc, v29, v0
	v_writelane_b32 v254, s1, 37
	v_writelane_b32 v254, s6, 38
	s_add_u32 s0, s12, 0x4000200
	v_lshlrev_b32_e32 v176, 2, v2
	v_writelane_b32 v254, s7, 39
	v_writelane_b32 v254, s4, 40
	v_cndmask_b32_e32 v2, v173, v29, vcc
	v_cmp_lt_i32_e32 vcc, v28, v0
	v_writelane_b32 v254, s5, 41
	v_writelane_b32 v254, s0, 42
	v_writelane_b32 v254, s12, 43
	s_addc_u32 s0, s13, 0
	s_mov_b32 s4, 0x18800
	v_writelane_b32 v254, s13, 44
	v_writelane_b32 v254, s0, 45
	s_lshl_b32 s0, s2, 7
	s_addk_i32 s0, 0xec00
	v_writelane_b32 v254, s0, 46
	s_lshl_b32 s0, s34, 7
	s_add_i32 s95, s0, 0xffffec00
	s_lshl_b32 s0, s2, 4
	s_addk_i32 s0, 0xfd80
	v_writelane_b32 v254, s0, 47
	s_addk_i32 s4, 0x120
	v_writelane_b32 v254, s4, 48
	s_mov_b32 s4, 0x14400
	s_addk_i32 s4, 0x120
	v_writelane_b32 v254, s4, 49
	s_lshl_b32 s1, s1, 2
	v_writelane_b32 v254, s1, 50
	v_sub_co_u32_e64 v193, s[4:5], s2, 40
	s_ashr_i32 s39, s38, 31
	s_nop 0
	v_writelane_b32 v254, s4, 51
	s_lshl_b64 s[66:67], s[38:39], 8
	v_lshlrev_b32_e32 v177, 2, v2
	v_writelane_b32 v254, s5, 52
	v_cmp_gt_u32_e64 s[4:5], s90, v193
	v_cndmask_b32_e32 v2, v173, v28, vcc
	v_cmp_lt_i32_e32 vcc, v27, v0
	v_writelane_b32 v254, s4, 53
	v_lshlrev_b32_e32 v178, 2, v2
	v_cndmask_b32_e32 v2, v173, v27, vcc
	v_writelane_b32 v254, s5, 54
	s_lshl_b64 s[4:5], s[34:35], 14
	v_writelane_b32 v254, s4, 55
	v_cmp_lt_i32_e32 vcc, v26, v0
	v_lshlrev_b32_e32 v179, 2, v2
	v_writelane_b32 v254, s5, 56
	s_mov_b64 s[4:5], -1
	v_writelane_b32 v254, s4, 57
	v_cndmask_b32_e32 v2, v173, v26, vcc
	v_cmp_lt_i32_e32 vcc, v1, v0
	v_writelane_b32 v254, s5, 58
	s_mov_b32 s4, s38
	v_writelane_b32 v254, s4, 59
	s_lshl_b32 s0, s34, 4
	v_cndmask_b32_e32 v0, v173, v1, vcc
	v_writelane_b32 v254, s5, 60
	v_writelane_b32 v254, s62, 61
	s_add_i32 s96, s0, 0xfffffd80
	s_mul_i32 s76, s76, s34
	v_writelane_b32 v254, s63, 62
	v_writelane_b32 v254, s66, 63
	v_lshlrev_b32_e32 v180, 2, v2
	v_lshlrev_b32_e32 v181, 2, v0
	v_writelane_b32 v255, s67, 0
	v_writelane_b32 v255, s84, 1
	s_movk_i32 s78, 0xc00
	s_mov_b32 s97, 0x1fffe0
	v_writelane_b32 v255, s85, 2
	v_writelane_b32 v255, s79, 3
	v_writelane_b32 v255, s92, 4
	v_writelane_b32 v255, s93, 5
	v_writelane_b32 v255, s94, 6
	v_writelane_b32 v255, s95, 7
	s_mov_b32 s44, 0x10000
	v_mov_b32_e32 v161, 0
	s_mov_b32 s45, 0x14000
	s_mov_b32 s46, 0x18000
	s_mov_b32 s47, 0x1c000
	v_mov_b32_e32 v182, 0x358637bd
	s_mov_b32 s50, 0xf800000
	v_mov_b32_e32 v183, 0x260
	s_movk_i32 s0, 0x80
	s_movk_i32 s75, 0x1400
	v_mov_b32_e32 v184, 0x1000
	v_mov_b32_e32 v185, 0x2000
	v_mov_b32_e32 v186, 0xf503000
	v_mov_b32_e32 v187, 1
	s_brev_b32 s30, -2
	s_brev_b32 s64, 18
	s_mov_b32 s74, 0xfe5163ab
	s_mov_b32 s77, 0x3c439041
	s_mov_b32 s82, 0xdb629599
	s_mov_b32 s83, 0xf534ddc0
	v_mov_b32_e32 v188, 0x3c0881c4
	v_mov_b32_e32 v189, 0xbab64f3b
	s_mov_b32 s31, 0x20000
	v_not_b32_e32 v190, 63
	v_not_b32_e32 v191, 31
	v_mov_b32_e32 v192, 0x7fc00000
	v_mov_b32_e32 v194, 0xc00
	v_mov_b32_e32 v195, 0x120
	v_mov_b32_e32 v196, 0x7f800000
	v_mov_b32_e32 v197, 0xff800000
	v_mov_b64_e32 v[162:163], 0xff
	v_mov_b64_e32 v[164:165], 0x100
	v_mov_b64_e32 v[166:167], 0x400
	v_mov_b64_e32 v[168:169], 0x3ff
	s_mov_b32 s33, 0xfc2757d1
	s_mov_b32 s54, 0x4e441529
	s_mov_b32 s55, 0xa2f9836e
	s_mov_b32 s86, 0x3fc90fda
	s_mov_b32 s87, 0x3f22f983
	s_mov_b32 s80, 0xbfc90fda
	s_movk_i32 s81, 0x1f8
	s_mov_b32 s65, 0x49800000
	s_mov_b32 s70, 0
	s_mov_b64 s[88:89], 0x80
	v_writelane_b32 v255, s96, 8
	s_branch .LBB0_108

.LBB0_326:
	s_or_b64 exec, exec, s[10:11]
	s_mov_b64 s[16:17], s[84:85]
	s_waitcnt lgkmcnt(0)
	v_mov_b32_e32 v0, v173
	s_barrier
	s_getreg_b32 s1, hwreg(HW_REG_HW_ID, 0, 7)
	s_and_b32 s1, s1, 63
	s_lshl_b32 s1, s1, 2
	v_mov_b32_e32 v1, s1
	ds_read_b32 v1, v1
	v_readlane_b32 s6, v254, 7
	v_readlane_b32 s7, v254, 8
	s_mov_b64 s[10:11], -1
	s_and_b64 vcc, exec, s[6:7]
	s_waitcnt lgkmcnt(0)
	v_readfirstlane_b32 s1, v1
	s_lshl_b32 s1, s1, 6
	s_and_b32 s1, s1, 0x3fc0
	v_add_u32_e32 v72, s1, v0
	s_cbranch_vccz .LBB0_335
	v_readlane_b32 s6, v254, 51
	v_readlane_b32 s7, v254, 52
	s_andn2_b64 vcc, exec, s[6:7]
	s_cbranch_vccnz .LBB0_334
	v_readfirstlane_b32 s42, v72
	s_cmpk_lt_u32 s42, 0x80
	s_cbranch_scc1 .Ls5_work
	s_cmpk_lt_u32 s42, 0x100
	s_cbranch_scc1 .LBB0_334
	s_load_dwordx2 s[42:43], s[16:17], 0xe0
	s_sub_u32 s48, s2, 32
	s_lshl_b32 s48, s48, 10
	v_and_b32_e32 v140, 0x3f, v72
	v_lshlrev_b32_e32 v140, 4, v140
	v_lshrrev_b32_e32 v141, 6, v72
	v_subrev_u32_e32 v141, 4, v141
	v_lshl_add_u32 v140, v141, 13, v140
	s_waitcnt lgkmcnt(0)
	s_add_u32 s42, s42, s48
	s_addc_u32 s43, s43, 0
	s_add_u32 s42, s42, 0xf100000
	s_addc_u32 s43, s43, 0
	s_movk_i32 s48, 64
.Lpf_s5:
	global_load_dwordx4 v[144:147], v140, s[42:43]
	s_add_u32 s42, s42, 0x8000
	s_addc_u32 s43, s43, 0
	s_sub_u32 s48, s48, 1
	s_cmp_lg_u32 s48, 0
	s_cbranch_scc1 .Lpf_s5
	s_branch .LBB0_334
.Ls5_work:
	s_lshl_b32 s1, s2, 7
	s_addk_i32 s1, 0xf000
	s_load_dwordx4 s[8:11], s[16:17], 0x30
	s_load_dwordx2 s[6:7], s[16:17], 0x40
	v_add_u32_e32 v4, s1, v72
	v_and_b32_e32 v1, 0xffffffc0, v4
	v_lshl_add_u32 v1, s70, 10, v1
	v_and_or_b32 v0, v0, 63, v1
	v_ashrrev_i32_e32 v1, 31, v0
	v_lshlrev_b64 v[0:1], 2, v[0:1]
	s_waitcnt lgkmcnt(0)
	v_lshl_add_u64 v[2:3], s[6:7], 0, v[0:1]
	global_load_dword v5, v[2:3], off
	v_lshl_add_u64 v[2:3], s[10:11], 0, v[0:1]
	global_load_dword v6, v[2:3], off
	v_lshl_add_u64 v[0:1], s[8:9], 0, v[0:1]
	global_load_dword v2, v[0:1], off
	s_waitcnt vmcnt(2)
	v_mul_f32_e32 v0, 0x3fb8aa3b, v5
	v_exp_f32_e32 v3, v0
	s_waitcnt vmcnt(1)
	v_mul_f32_e32 v0, v6, v3
	v_and_b32_e32 v1, 0x7fffffff, v0
	v_cmp_nlt_f32_e64 s[6:7], |v0|, s64
	s_and_saveexec_b64 s[8:9], s[6:7]
	s_xor_b64 s[18:19], exec, s[8:9]
	s_cbranch_execz .LBB0_330
	v_lshrrev_b32_e32 v5, 23, v1
	v_add_u32_e32 v5, 0xffffff88, v5
	v_cmp_lt_u32_e32 vcc, 63, v5
	s_nop 1
	v_cndmask_b32_e32 v6, 0, v190, vcc
	v_add_u32_e32 v5, v6, v5
	v_cmp_lt_u32_e64 s[10:11], 31, v5
	s_nop 1
	v_cndmask_b32_e64 v6, 0, v191, s[10:11]
	v_add_u32_e32 v5, v6, v5
	v_cmp_lt_u32_e64 s[12:13], 31, v5
	s_nop 1
	v_cndmask_b32_e64 v6, 0, v191, s[12:13]
	v_add_u32_e32 v5, v6, v5
	v_and_b32_e32 v6, 0x7fffff, v1
	v_or_b32_e32 v18, 0x800000, v6
	v_mad_u64_u32 v[6:7], s[6:7], v18, s74, 0
	v_mov_b32_e32 v160, v7
	v_mad_u64_u32 v[8:9], s[6:7], v18, s77, v[160:161]
	v_mov_b32_e32 v160, v9
	v_mad_u64_u32 v[10:11], s[6:7], v18, s82, v[160:161]
	v_mov_b32_e32 v160, v11
	v_mad_u64_u32 v[12:13], s[6:7], v18, s83, v[160:161]
	v_mov_b32_e32 v160, v13
	v_mad_u64_u32 v[14:15], s[6:7], v18, s33, v[160:161]
	v_mov_b32_e32 v160, v15
	v_mad_u64_u32 v[16:17], s[6:7], v18, s54, v[160:161]
	v_mov_b32_e32 v160, v17
	v_mad_u64_u32 v[18:19], s[6:7], v18, s55, v[160:161]
	v_cndmask_b32_e32 v7, v16, v12, vcc
	v_cndmask_b32_e32 v9, v18, v14, vcc
	v_cndmask_b32_e32 v13, v19, v16, vcc
	v_cndmask_b32_e64 v11, v9, v7, s[10:11]
	v_cndmask_b32_e64 v9, v13, v9, s[10:11]
	v_cndmask_b32_e32 v13, v14, v10, vcc
	v_cndmask_b32_e64 v7, v7, v13, s[10:11]
	v_sub_u32_e32 v14, 32, v5
	v_cmp_eq_u32_e64 s[14:15], 0, v5
	v_cndmask_b32_e32 v5, v12, v8, vcc
	v_cndmask_b32_e64 v9, v9, v11, s[12:13]
	v_cndmask_b32_e64 v11, v11, v7, s[12:13]
	v_cndmask_b32_e64 v8, v13, v5, s[10:11]
	v_alignbit_b32 v15, v9, v11, v14
	v_cndmask_b32_e64 v7, v7, v8, s[12:13]
	v_cndmask_b32_e64 v9, v15, v9, s[14:15]
	v_alignbit_b32 v12, v11, v7, v14
	v_cndmask_b32_e32 v6, v10, v6, vcc
	v_cndmask_b32_e64 v11, v12, v11, s[14:15]
	v_bfe_u32 v15, v9, 29, 1
	v_cndmask_b32_e64 v5, v5, v6, s[10:11]
	v_alignbit_b32 v12, v9, v11, 30
	v_sub_u32_e32 v16, 0, v15
	v_cndmask_b32_e64 v5, v8, v5, s[12:13]
	v_xor_b32_e32 v12, v12, v16
	v_alignbit_b32 v6, v7, v5, v14
	v_cndmask_b32_e64 v6, v6, v7, s[14:15]
	v_ffbh_u32_e32 v8, v12
	v_alignbit_b32 v7, v11, v6, 30
	v_min_u32_e32 v8, 32, v8
	v_alignbit_b32 v5, v6, v5, 30
	v_xor_b32_e32 v7, v7, v16
	v_sub_u32_e32 v10, 31, v8
	v_xor_b32_e32 v5, v5, v16
	v_alignbit_b32 v11, v12, v7, v10
	v_alignbit_b32 v5, v7, v5, v10
	v_alignbit_b32 v6, v11, v5, 9
	v_ffbh_u32_e32 v7, v6
	v_min_u32_e32 v7, 32, v7
	v_lshrrev_b32_e32 v13, 29, v9
	v_not_b32_e32 v10, v7
	v_alignbit_b32 v5, v6, v5, v10
	v_lshlrev_b32_e32 v6, 31, v13
	v_or_b32_e32 v10, 0x33000000, v6
	v_add_lshl_u32 v7, v7, v8, 23
	v_lshrrev_b32_e32 v5, 9, v5
	v_sub_u32_e32 v7, v10, v7
	v_or_b32_e32 v6, 0.5, v6
	v_lshlrev_b32_e32 v8, 23, v8
	v_or_b32_e32 v5, v7, v5
	v_lshrrev_b32_e32 v7, 9, v11
	v_sub_u32_e32 v6, v6, v8
	v_or_b32_e32 v6, v7, v6
	v_mul_f32_e32 v7, 0x3fc90fda, v6
	v_fma_f32 v8, v6, s86, -v7
	v_fmac_f32_e32 v8, 0x33a22168, v6
	v_fmac_f32_e32 v8, 0x3fc90fda, v5
	v_lshrrev_b32_e32 v6, 30, v9
	v_add_f32_e32 v5, v7, v8
	v_add_u32_e32 v6, v15, v6
